# grid barrier: XCD leader bumps the per-XCD generation before its own cache invalidate (members released earlier); plus WTg fill loads issued together
# baseline (speedup 1.0000x reference)
.LBB0_571:
	s_and_b64 vcc, exec, s[0:1]
	s_cbranch_vccz .LBB0_506
	s_and_b32 s8, s20, 7
	s_lshl_b32 s18, s8, 6
	s_lshl_b32 s2, s8, 8
	s_waitcnt vmcnt(0)
	v_and_b32_e32 v4, 15, v52
	s_add_u32 s0, s10, s2
	s_addc_u32 s1, s11, 0
	v_lshlrev_b32_e32 v0, 4, v4
	global_load_dwordx4 v[24:27], v0, s[0:1]
	s_add_u32 s0, s12, s2
	s_addc_u32 s1, s13, 0
	s_waitcnt lgkmcnt(0)
	global_load_dwordx4 v[32:35], v0, s[0:1]
	s_add_u32 s0, s14, s2
	s_addc_u32 s1, s15, 0
	global_load_dwordx4 v[16:19], v0, s[0:1]
	s_add_u32 s0, s16, s2
	s_addc_u32 s1, s17, 0
	global_load_dwordx4 v[20:23], v0, s[0:1]
	s_movk_i32 s0, 0x2000
	v_cmp_gt_i32_e32 vcc, s0, v52
	s_and_saveexec_b64 s[0:1], vcc
	s_cbranch_execz .LBB0_582
	v_readlane_b32 s2, v254, 13
	v_and_b32_e32 v2, 63, v52
	v_lshrrev_b32_e32 v3, 6, v52
	s_movk_i32 s3, 0x110
	v_mov_b32_e32 v0, s2
	v_mad_u32_u24 v5, v2, s3, v0
	v_lshl_add_u32 v5, v3, 1, v5
	v_lshl_or_b32 v0, v3, 9, v2
	v_or_b32_e32 v0, s18, v0
	v_lshlrev_b32_e32 v0, 2, v0
	s_mov_b64 s[2:3], s[60:61]
	global_load_dword v36, v0, s[2:3]
	s_add_u32 s2, s2, 0x4000
	s_addc_u32 s3, s3, 0
	global_load_dword v37, v0, s[2:3]
	s_add_u32 s2, s2, 0x4000
	s_addc_u32 s3, s3, 0
	global_load_dword v38, v0, s[2:3]
	s_add_u32 s2, s2, 0x4000
	s_addc_u32 s3, s3, 0
	global_load_dword v39, v0, s[2:3]
	s_add_u32 s2, s2, 0x4000
	s_addc_u32 s3, s3, 0
	global_load_dword v40, v0, s[2:3]
	s_add_u32 s2, s2, 0x4000
	s_addc_u32 s3, s3, 0
	global_load_dword v41, v0, s[2:3]
	s_add_u32 s2, s2, 0x4000
	s_addc_u32 s3, s3, 0
	global_load_dword v42, v0, s[2:3]
	s_add_u32 s2, s2, 0x4000
	s_addc_u32 s3, s3, 0
	global_load_dword v43, v0, s[2:3]
	s_add_u32 s2, s2, 0x4000
	s_addc_u32 s3, s3, 0
	global_load_dword v44, v0, s[2:3]
	s_add_u32 s2, s2, 0x4000
	s_addc_u32 s3, s3, 0
	global_load_dword v45, v0, s[2:3]
	s_add_u32 s2, s2, 0x4000
	s_addc_u32 s3, s3, 0
	global_load_dword v46, v0, s[2:3]
	s_add_u32 s2, s2, 0x4000
	s_addc_u32 s3, s3, 0
	global_load_dword v47, v0, s[2:3]
	s_add_u32 s2, s2, 0x4000
	s_addc_u32 s3, s3, 0
	global_load_dword v48, v0, s[2:3]
	s_add_u32 s2, s2, 0x4000
	s_addc_u32 s3, s3, 0
	global_load_dword v49, v0, s[2:3]
	s_add_u32 s2, s2, 0x4000
	s_addc_u32 s3, s3, 0
	global_load_dword v50, v0, s[2:3]
	s_add_u32 s2, s2, 0x4000
	s_addc_u32 s3, s3, 0
	global_load_dword v51, v0, s[2:3]
	s_movk_i32 s9, 0x7fff
	s_movk_i32 s5, 0x7fff
	s_waitcnt vmcnt(0)
	v_bfe_u32 v1, v36, 16, 1
	v_bfe_u32 v2, v37, 16, 1
	v_add3_u32 v36, v36, v1, s9
	v_add3_u32 v37, v37, v2, s9
	ds_write_b16_d16_hi v5, v36 offset:0
	ds_write_b16_d16_hi v5, v37 offset:16
	v_bfe_u32 v1, v38, 16, 1
	v_bfe_u32 v2, v39, 16, 1
	v_add3_u32 v38, v38, v1, s9
	v_add3_u32 v39, v39, v2, s9
	ds_write_b16_d16_hi v5, v38 offset:32
	ds_write_b16_d16_hi v5, v39 offset:48
	v_bfe_u32 v1, v40, 16, 1
	v_bfe_u32 v2, v41, 16, 1
	v_add3_u32 v40, v40, v1, s9
	v_add3_u32 v41, v41, v2, s9
	ds_write_b16_d16_hi v5, v40 offset:64
	ds_write_b16_d16_hi v5, v41 offset:80
	v_bfe_u32 v1, v42, 16, 1
	v_bfe_u32 v2, v43, 16, 1
	v_add3_u32 v42, v42, v1, s9
	v_add3_u32 v43, v43, v2, s9
	ds_write_b16_d16_hi v5, v42 offset:96
	ds_write_b16_d16_hi v5, v43 offset:112
	v_bfe_u32 v1, v44, 16, 1
	v_bfe_u32 v2, v45, 16, 1
	v_add3_u32 v44, v44, v1, s9
	v_add3_u32 v45, v45, v2, s9
	ds_write_b16_d16_hi v5, v44 offset:128
	ds_write_b16_d16_hi v5, v45 offset:144
	v_bfe_u32 v1, v46, 16, 1
	v_bfe_u32 v2, v47, 16, 1
	v_add3_u32 v46, v46, v1, s9
	v_add3_u32 v47, v47, v2, s9
	ds_write_b16_d16_hi v5, v46 offset:160
	ds_write_b16_d16_hi v5, v47 offset:176
	v_bfe_u32 v1, v48, 16, 1
	v_bfe_u32 v2, v49, 16, 1
	v_add3_u32 v48, v48, v1, s9
	v_add3_u32 v49, v49, v2, s9
	ds_write_b16_d16_hi v5, v48 offset:192
	ds_write_b16_d16_hi v5, v49 offset:208
	v_bfe_u32 v1, v50, 16, 1
	v_bfe_u32 v2, v51, 16, 1
	v_add3_u32 v50, v50, v1, s9
	v_add3_u32 v51, v51, v2, s9
	ds_write_b16_d16_hi v5, v50 offset:224
	ds_write_b16_d16_hi v5, v51 offset:240

.LBB0_1533:
	s_or_b64 exec, exec, s[2:3]
	s_mov_b64 s[2:3], exec
	v_mbcnt_lo_u32_b32 v0, s2, 0
	v_mbcnt_hi_u32_b32 v0, s3, v0
	v_cmp_eq_u32_e32 vcc, 0, v0
	s_waitcnt vmcnt(0)
	s_and_saveexec_b64 s[4:5], vcc
	s_cbranch_execz .LBB0_1535
	s_bcnt1_i32_b64 s2, s[2:3]
	v_mov_b32_e32 v0, s2
	v_readlane_b32 s2, v251, 22
	v_readlane_b32 s3, v251, 23
	s_nop 4
	global_atomic_add v31, v0, s[2:3]
.LBB0_1535:
	s_or_b64 exec, exec, s[4:5]
	buffer_inv sc1
	s_waitcnt vmcnt(0)
